# P4 chain loop: one static priority raise for the younger waves (4-7)
# baseline (speedup 1.0000x reference)
.Lp4n_tab:
	v_mbcnt_lo_u32_b32 v229, -1, 0
	v_mbcnt_hi_u32_b32 v229, -1, v229
	v_and_b32_e32 v230, s61, v229
	v_lshrrev_b32_e32 v231, s62, v229
	v_lshrrev_b32_e32 v232, 1, v231
	v_add_u32_e32 v232, s59, v232
	v_and_b32_e32 v232, 7, v232
	v_add_u32_e32 v233, s60, v231
	v_and_b32_e32 v233, 1, v233
	v_sub_u32_e32 v234, s61, v230
	v_cmp_eq_u32_e32 vcc, 1, v233
	s_nop 1
	v_cndmask_b32_e32 v235, v230, v234, vcc
	v_add_u32_e32 v235, s64, v235
	v_cmp_eq_u32_e32 vcc, s61, v230
	s_nop 1
	v_cndmask_b32_e64 v236, 0, 1, vcc
	v_lshlrev_b32_e32 v237, 9, v232
	v_or_b32_e32 v220, v235, v237
	v_lshlrev_b32_e32 v237, 12, v233
	v_or_b32_e32 v220, v220, v237
	s_lshl_b32 s45, s57, 13
	s_lshl_b32 s46, s58, 15
	s_or_b32 s45, s45, s46
	s_lshl_b32 s46, s63, 20
	s_or_b32 s45, s45, s46
	v_or_b32_e32 v220, s45, v220
	v_lshlrev_b32_e32 v237, 21, v236
	v_or_b32_e32 v220, v220, v237
	v_lshlrev_b32_e32 v237, 22, v230
	v_or_b32_e32 v220, v220, v237
	v_lshl_add_u32 v237, v235, 3, v232
	v_lshlrev_b32_e32 v221, 14, v237
	v_lshlrev_b32_e32 v238, 8, v233
	v_lshl_add_u32 v224, v237, 10, v238
	v_lshlrev_b32_e32 v238, 8, v232
	v_lshl_add_u32 v222, v235, 17, v238
	s_mov_b32 s45, 0xc0000
	v_mul_lo_u32 v237, v235, s45
	s_lshl_b32 s46, s57, 6
	s_sub_u32 s46, s46, 0x5000
	v_add_u32_e32 v238, s46, v238
	v_add_u32_e32 v223, v237, v238
	s_mov_b32 s45, 0x60000
	v_mul_lo_u32 v237, v235, s45
	v_lshlrev_b32_e32 v238, 10, v233
	v_lshl_add_u32 v238, v232, 7, v238
	s_lshl_b32 s46, s57, 5
	v_add_u32_e32 v238, s46, v238
	v_add_u32_e32 v227, v237, v238
	v_lshlrev_b32_e32 v228, 6, v235
	v_mov_b32_e32 v225, s65
	v_mov_b32_e32 v226, s66
	s_mov_b32 s99, 0
	s_cmp_lt_u32 s97, 4
	s_cbranch_scc1 .Lp4n_noprio
	s_setprio 1
.Lp4n_noprio:
	v_lshlrev_b32_e32 v253, 2, v189
	v_add_u32_e32 v254, 0x1d900, v253
	v_add_u32_e32 v253, 0x1d400, v253
	v_add_u32_e32 v197, v173, v182
	v_mov_b32_e32 v251, 0x1d400
	v_mov_b32_e32 v252, 0x1d900
	v_add_u32_e32 v255, 0x1da00, v180
	v_add_u32_e32 v247, 0x3000, v120
	v_add_u32_e32 v248, 0x6000, v120
	v_add_u32_e32 v249, 0x9000, v120
	v_lshlrev_b32_e32 v239, 4, v0
	v_add_u32_e32 v240, 0x2000, v239
	v_mov_b32_e32 v241, v118
	v_add_u32_e32 v242, 0x10000, v118
	s_mov_b32 s100, 0xbfb8aa3b
	s_mov_b32 s101, 0xbfb8aa3b
	s_nop 1
	v_readlane_b32 s41, v220, 0
	v_readlane_b32 s42, v220, 1
	v_readlane_b32 s43, v220, 2

.Lp4n_exit:
	s_setprio 0
	v_readlane_b32 s10, v250, 0
	v_readlane_b32 s11, v250, 1
	s_load_dwordx2 s[64:65], s[10:11], 0xc8
	s_mov_b32 s66, s96
	s_cmpk_lt_u32 s66, 0x80
	s_cbranch_scc0 .Lp4scan_done
	s_waitcnt vmcnt(0)
	v_add_u32_e32 v2, 0xfffffee0, v0
	s_movk_i32 s0, 0xffdf
	v_cmp_lt_u32_e32 vcc, s0, v2
	s_and_saveexec_b64 s[0:1], vcc
	s_cbranch_execz .Lp4scan_559
	v_lshl_add_u32 v2, s66, 5, v0
	s_movk_i32 s2, 0x1100
	v_cmp_gt_i32_e32 vcc, s2, v2
	s_and_b64 exec, exec, vcc
	s_cbranch_execz .Lp4scan_559
	v_readlane_b32 s2, v250, 0
	v_readlane_b32 s3, v250, 1
	v_add_u32_e32 v2, 0xffffff00, v2
	s_load_dwordx2 s[2:3], s[2:3], 0x18
	v_bfe_u32 v9, v2, 10, 1
	v_ashrrev_i32_e32 v8, 11, v2
	v_and_b32_e32 v6, 0x3ff, v2
	v_lshlrev_b32_e32 v4, 13, v9
	v_mov_b32_e32 v5, 0
	v_lshl_add_u64 v[2:3], s[74:75], 0, v[4:5]
	v_lshlrev_b32_e32 v4, 2, v6
	v_lshl_or_b32 v6, v8, 1, v9
	v_ashrrev_i32_e32 v7, 31, v6
	v_lshlrev_b64 v[6:7], 12, v[6:7]
	s_waitcnt lgkmcnt(0)
	v_lshl_add_u64 v[6:7], s[2:3], 0, v[6:7]
	v_lshl_add_u64 v[6:7], v[6:7], 0, v[4:5]
	global_load_dword v10, v[6:7], off
	v_lshlrev_b32_e32 v6, 12, v9
	v_mov_b32_e32 v7, v5
	v_lshl_add_u64 v[2:3], v[2:3], 0, v[4:5]
	s_mov_b64 s[2:3], 0x4b4000
	v_lshl_add_u64 v[6:7], s[74:75], 0, v[6:7]
	v_lshlrev_b32_e32 v11, 6, v8
	v_lshl_add_u64 v[2:3], v[2:3], 0, s[2:3]
	v_lshl_add_u64 v[4:5], v[6:7], 0, v[4:5]
	s_mov_b64 s[2:3], 0xf9c4000
	v_add_u32_e32 v8, 0x80, v11
	v_lshl_add_u64 v[4:5], v[4:5], 0, s[2:3]
	s_mov_b32 s8, 0
	v_cmp_eq_u32_e64 s[4:5], 0, v9
	v_add_u32_e32 v9, 0xbf, v11
	s_mov_b64 s[2:3], -1
	s_mov_b32 s9, 0
